# attention steady loop: redundant canonicalising v_max, +0 adds and loop-invariant v_mov removed/hoisted
# speedup vs baseline: 1.0329x; 1.0024x over previous
.LBB0_357:
	v_lshlrev_b32_e32 v36, 1, v34
	v_lshlrev_b32_e32 v34, 4, v34
	v_and_b32_e32 v244, 32, v36
	v_and_b32_e32 v34, 0xc0, v34
	v_lshl_or_b32 v241, v239, 8, v34
	v_add_u32_e32 v34, 0, v244
	v_mul_f32_e32 v35, 0xc2800000, v212
	v_add3_u32 v249, v34, v240, v241
	v_max3_f32 v34, v2, v3, v18
	v_exp_f32_e32 v210, v35
	v_max3_f32 v35, v4, v5, v19
	v_max3_f32 v34, v34, v20, v21
	v_mov_b32_e32 v213, v212
	v_max3_f32 v34, v34, v6, v7
	v_max3_f32 v35, v35, v8, v9
	s_and_b32 s1, s48, 0x3fffffc0
	v_max3_f32 v34, v34, v22, v23
	v_max3_f32 v35, v35, v24, v25
	s_lshl_b32 s1, s1, 2
	v_max3_f32 v34, v34, v10, v11
	v_max3_f32 v35, v35, v12, v13
	s_add_i32 s48, s1, 0
	v_max3_f32 v34, v34, v26, v27
	v_max3_f32 v35, v35, v28, v29
	s_cmp_lg_u32 0, -1
	v_max3_f32 v34, v34, v14, v15
	v_max3_f32 v35, v35, v16, v17
	s_mov_b32 s50, 1
	v_max3_f32 v34, v34, v30, v31
	v_max3_f32 v35, v35, v32, v33
	s_mov_b32 s1, 0
	v_max_f32_e32 v34, v34, v35
	s_mov_b32 s51, 0
	v_mov_b32_e32 v35, v34
	s_nop 1
	v_permlane32_swap_b32_e32 v34, v35
	v_max_f32_e32 v34, v34, v35
	v_mov_b32_e32 v220, v214
	v_add_f32_e32 v247, v207, v34
	v_sub_f32_e32 v35, v2, v34
	v_sub_f32_e32 v3, v3, v34
	v_sub_f32_e32 v18, v18, v34
	v_sub_f32_e32 v19, v19, v34
	v_sub_f32_e32 v4, v4, v34
	s_nop 0
	v_sub_f32_e32 v2, v206, v247
	v_fma_f32 v66, 0, v212, v2
	v_add_f32_e32 v67, v212, v2
	v_pk_fma_f32 v[68:69], v[212:213], s[86:87], v[2:3] op_sel_hi:[1,1,0]
	v_pk_fma_f32 v[70:71], v[212:213], s[88:89], v[2:3] op_sel_hi:[1,1,0]
	v_pk_fma_f32 v[72:73], v[212:213], s[90:91], v[2:3] op_sel_hi:[1,1,0]
	v_pk_fma_f32 v[74:75], v[212:213], s[92:93], v[2:3] op_sel_hi:[1,1,0]
	v_pk_fma_f32 v[76:77], v[212:213], s[94:95], v[2:3] op_sel_hi:[1,1,0]
	v_pk_fma_f32 v[78:79], v[212:213], s[96:97], v[2:3] op_sel_hi:[1,1,0]
	v_pk_fma_f32 v[80:81], v[212:213], s[16:17], v[2:3] op_sel_hi:[1,1,0]
	v_exp_f32_e32 v83, v3
	s_waitcnt vmcnt(0) lgkmcnt(0)
	s_barrier
	v_lshl_add_u64 v[2:3], v[216:217], 0, s[74:75]
	s_mov_b32 s6, m0
	s_mov_b32 m0, s29
	s_nop 0
	global_load_lds_dwordx4 v[2:3], off
	s_mov_b32 m0, s6
	s_cselect_b32 s6, 0, 0
	s_add_i32 s6, s6, s46
	v_lshl_add_u64 v[2:3], v[218:219], 0, s[78:79]
	s_add_i32 s6, s6, 0x8000
	s_mov_b32 s7, m0
	s_mov_b32 m0, s6
	s_nop 0
	global_load_lds_dwordx4 v[2:3], off
	s_mov_b32 m0, s7
	ds_read_b128 v[190:193], v248 offset:8192
	ds_read_b128 v[186:189], v248 offset:8704
	ds_read_b128 v[182:185], v248 offset:10240
	ds_read_b128 v[178:181], v248 offset:10752
	ds_read_b128 v[174:177], v248 offset:12288
	ds_read_b128 v[170:173], v248 offset:12800
	ds_read_b128 v[166:169], v248 offset:14336
	ds_read_b128 v[162:165], v248 offset:14848
	v_sub_f32_e32 v20, v20, v34
	v_sub_f32_e32 v5, v5, v34
	v_sub_f32_e32 v21, v21, v34
	v_sub_f32_e32 v6, v6, v34
	v_sub_f32_e32 v22, v22, v34
	v_sub_f32_e32 v7, v7, v34
	v_sub_f32_e32 v23, v23, v34
	v_sub_f32_e32 v8, v8, v34
	v_sub_f32_e32 v24, v24, v34
	v_sub_f32_e32 v9, v9, v34
	v_sub_f32_e32 v25, v25, v34
	v_sub_f32_e32 v10, v10, v34
	v_sub_f32_e32 v26, v26, v34
	v_sub_f32_e32 v11, v11, v34
	v_sub_f32_e32 v27, v27, v34
	v_sub_f32_e32 v12, v12, v34
	v_sub_f32_e32 v28, v28, v34
	v_sub_f32_e32 v13, v13, v34
	v_sub_f32_e32 v29, v29, v34
	v_sub_f32_e32 v14, v14, v34
	v_sub_f32_e32 v30, v30, v34
	v_sub_f32_e32 v15, v15, v34
	v_sub_f32_e32 v31, v31, v34
	v_sub_f32_e32 v16, v16, v34
	v_sub_f32_e32 v32, v32, v34
	v_sub_f32_e32 v17, v17, v34
	v_sub_f32_e32 v33, v33, v34
	v_exp_f32_e32 v82, v35
	v_exp_f32_e32 v84, v4
	v_exp_f32_e32 v85, v5
	v_exp_f32_e32 v86, v6
	v_exp_f32_e32 v87, v7
	v_exp_f32_e32 v88, v8
	v_exp_f32_e32 v89, v9
	v_exp_f32_e32 v90, v10
	v_exp_f32_e32 v91, v11
	v_exp_f32_e32 v92, v12
	v_exp_f32_e32 v93, v13
	v_exp_f32_e32 v94, v14
	v_exp_f32_e32 v95, v15
	v_exp_f32_e32 v96, v16
	v_exp_f32_e32 v97, v17
	v_exp_f32_e32 v98, v18
	v_exp_f32_e32 v99, v19
	v_exp_f32_e32 v100, v20
	v_exp_f32_e32 v101, v21
	v_exp_f32_e32 v102, v22
	v_exp_f32_e32 v103, v23
	v_exp_f32_e32 v104, v24
	v_exp_f32_e32 v105, v25
	v_exp_f32_e32 v106, v26
	v_exp_f32_e32 v107, v27
	v_exp_f32_e32 v108, v28
	v_exp_f32_e32 v109, v29
	v_exp_f32_e32 v110, v30
	v_exp_f32_e32 v111, v31
	v_exp_f32_e32 v112, v32
	v_exp_f32_e32 v113, v33
	s_waitcnt vmcnt(2) lgkmcnt(0)
	s_barrier
	s_cmp_lt_i32 s45, 7
	v_mov_b32_e32 v221, v214
	v_cmp_gt_u32_e64 s[6:7], 32, v209
	v_lshl_add_u32 v243, v238, 2, s48
	v_lshl_add_u32 v242, v245, 2, s48
	s_cbranch_scc1 .LBB0_379
	s_mov_b64 s[48:49], 0xa0000
	v_mov_b32_e32 v34, 0
	v_mov_b32_e32 v64, v210
	v_mov_b32_e32 v65, v210
	v_lshl_add_u64 v[222:223], v[218:219], 0, s[74:75]
	v_lshl_add_u64 v[224:225], v[216:217], 0, s[48:49]
	s_movk_i32 s1, 0x4000
	s_movk_i32 s50, 0x2000
	s_mov_b32 s49, 6
	v_mov_b32_e32 v2, 0
	v_mov_b32_e32 v3, v34
	v_mov_b32_e32 v4, v34
	v_mov_b32_e32 v5, v34
	v_mov_b32_e32 v6, v34
	v_mov_b32_e32 v7, v34
	v_mov_b32_e32 v8, v34
	v_mov_b32_e32 v9, v34
	v_mov_b32_e32 v10, v34
	v_mov_b32_e32 v11, v34
	v_mov_b32_e32 v12, v34
	v_mov_b32_e32 v13, v34
	v_mov_b32_e32 v14, v34
	v_mov_b32_e32 v15, v34
	v_mov_b32_e32 v16, v34
	v_mov_b32_e32 v17, v34
	v_mov_b32_e32 v18, 0
	v_mov_b32_e32 v19, v34
	v_mov_b32_e32 v20, v34
	v_mov_b32_e32 v21, v34
	v_mov_b32_e32 v22, v34
	v_mov_b32_e32 v23, v34
	v_mov_b32_e32 v24, v34
	v_mov_b32_e32 v25, v34
	v_mov_b32_e32 v26, v34
	v_mov_b32_e32 v27, v34
	v_mov_b32_e32 v28, v34
	v_mov_b32_e32 v29, v34
	v_mov_b32_e32 v30, v34
	v_mov_b32_e32 v31, v34
	v_mov_b32_e32 v32, v34
	v_mov_b32_e32 v33, v34
	v_mov_b32_e32 v215, v214
	v_mov_b32_e32 v211, v210
.LBB0_359:
	v_add_u32_e32 v35, s51, v249
	ds_read_b64_tr_b16 v[194:195], v35 offset:24576
	ds_read_b64_tr_b16 v[196:197], v35 offset:25088
	v_add_f32_e32 v36, v82, v83
	v_add_f32_e32 v36, v84, v36
	v_add_f32_e32 v36, v85, v36
	v_add_f32_e32 v36, v86, v36
	v_add_f32_e32 v52, v87, v36
	s_waitcnt lgkmcnt(9)
	v_mfma_f32_32x32x16_bf16 v[36:51], v[190:193], v[150:153], v[66:81]
	v_cvt_pk_bf16_f32 v158, v82, v83
	v_cvt_pk_bf16_f32 v159, v84, v85
	ds_read_b64_tr_b16 v[60:61], v35 offset:28672
	ds_read_b64_tr_b16 v[62:63], v35 offset:29184
	v_add_f32_e32 v52, v88, v52
	v_add_f32_e32 v52, v89, v52
	v_add_f32_e32 v52, v90, v52
	v_add_f32_e32 v56, v91, v52
	v_cvt_pk_bf16_f32 v160, v86, v87
	v_cvt_pk_bf16_f32 v161, v88, v89
	s_waitcnt lgkmcnt(10)
	v_mfma_f32_32x32x16_bf16 v[114:129], v[186:189], v[150:153], v[66:81]
	ds_read_b64_tr_b16 v[52:53], v35 offset:25600
	ds_read_b64_tr_b16 v[54:55], v35 offset:26112
	s_waitcnt lgkmcnt(11)
	v_mfma_f32_32x32x16_bf16 v[36:51], v[182:185], v[142:145], v[36:51]
	v_add_f32_e32 v56, v92, v56
	v_add_f32_e32 v56, v93, v56
	v_add_f32_e32 v56, v94, v56
	v_add_f32_e32 v82, v95, v56
	v_cvt_pk_bf16_f32 v154, v90, v91
	v_cvt_pk_bf16_f32 v155, v92, v93
	ds_read_b64_tr_b16 v[56:57], v35 offset:29696
	ds_read_b64_tr_b16 v[58:59], v35 offset:30208
	v_add_f32_e32 v82, v96, v82
	v_add_f32_e32 v82, v97, v82
	v_add_f32_e32 v82, v98, v82
	v_add_f32_e32 v86, v99, v82
	v_cvt_pk_bf16_f32 v156, v94, v95
	v_cvt_pk_bf16_f32 v157, v96, v97
	s_waitcnt lgkmcnt(12)
	v_mfma_f32_32x32x16_bf16 v[114:129], v[178:181], v[142:145], v[114:129]
	ds_read_b64_tr_b16 v[82:83], v35 offset:26624
	ds_read_b64_tr_b16 v[84:85], v35 offset:27136
	s_waitcnt lgkmcnt(13)
	v_mfma_f32_32x32x16_bf16 v[36:51], v[174:177], v[134:137], v[36:51]
	v_add_f32_e32 v86, v100, v86
	v_add_f32_e32 v86, v101, v86
	v_add_f32_e32 v86, v102, v86
	v_add_f32_e32 v90, v103, v86
	v_cvt_pk_bf16_f32 v146, v98, v99
	v_cvt_pk_bf16_f32 v147, v100, v101
	ds_read_b64_tr_b16 v[86:87], v35 offset:30720
	ds_read_b64_tr_b16 v[88:89], v35 offset:31232
	v_add_f32_e32 v90, v104, v90
	v_add_f32_e32 v90, v105, v90
	v_add_f32_e32 v90, v106, v90
	v_add_f32_e32 v94, v107, v90
	v_cvt_pk_bf16_f32 v148, v102, v103
	v_cvt_pk_bf16_f32 v149, v104, v105
	s_waitcnt lgkmcnt(14)
	v_mfma_f32_32x32x16_bf16 v[114:129], v[170:173], v[134:137], v[114:129]
	ds_read_b64_tr_b16 v[90:91], v35 offset:27648
	ds_read_b64_tr_b16 v[92:93], v35 offset:28160
	s_waitcnt lgkmcnt(14)
	v_mfma_f32_32x32x16_bf16 v[36:51], v[166:169], v[130:133], v[36:51]
	v_add_f32_e32 v94, v108, v94
	v_add_f32_e32 v94, v109, v94
	v_add_f32_e32 v94, v110, v94
	v_add_f32_e32 v98, v111, v94
	v_cvt_pk_bf16_f32 v138, v106, v107
	v_cvt_pk_bf16_f32 v139, v108, v109
	ds_read_b64_tr_b16 v[94:95], v35 offset:31744
	ds_read_b64_tr_b16 v[96:97], v35 offset:32256
	v_add_f32_e32 v35, v112, v98
	v_add_f32_e32 v35, v113, v35
	v_cvt_pk_bf16_f32 v140, v110, v111
	v_cvt_pk_bf16_f32 v141, v112, v113
	v_mfma_f32_32x32x16_bf16 v[114:129], v[162:165], v[130:133], v[114:129]
	v_lshl_add_u64 v[98:99], v[224:225], 0, s[80:81]
	s_add_i32 s46, s50, s29
	s_mov_b32 s48, m0
	s_mov_b32 m0, s46
	s_nop 0
	global_load_lds_dwordx4 v[98:99], off
	s_mov_b32 m0, s48
	v_lshl_add_u64 v[98:99], v[222:223], 0, s[80:81]
	s_add_i32 s46, s1, s44
	s_mov_b32 s48, m0
	s_mov_b32 m0, s46
	s_nop 0
	global_load_lds_dwordx4 v[98:99], off
	s_mov_b32 m0, s48
	s_nop 6
	v_pk_add_f32 v[98:99], v[220:221], v[114:115]
	v_pk_add_f32 v[100:101], v[214:215], v[116:117]
	v_max_f32_e32 v114, v36, v37
	v_max3_f32 v115, v38, v39, v99
	v_max3_f32 v114, v114, v98, v100
	v_pk_add_f32 v[104:105], v[214:215], v[120:121]
	v_pk_add_f32 v[102:103], v[214:215], v[118:119]
	v_max3_f32 v114, v114, v101, v40
	v_max3_f32 v115, v115, v42, v43
	v_max3_f32 v114, v114, v41, v102
	v_max3_f32 v115, v115, v104, v105
	v_pk_add_f32 v[108:109], v[214:215], v[124:125]
	v_pk_add_f32 v[106:107], v[214:215], v[122:123]
	v_max3_f32 v114, v114, v103, v44
	v_max3_f32 v115, v115, v46, v47
	v_max3_f32 v114, v114, v45, v106
	v_max3_f32 v115, v115, v108, v109
	v_pk_add_f32 v[112:113], v[214:215], v[128:129]
	v_pk_add_f32 v[110:111], v[214:215], v[126:127]
	v_max3_f32 v114, v114, v107, v48
	v_max3_f32 v115, v115, v50, v51
	v_max3_f32 v114, v114, v49, v110
	v_max3_f32 v115, v115, v112, v113
	v_add_f32_e32 v186, v34, v35
	v_max3_f32 v34, v114, v111, v115
	v_mov_b32_e32 v35, v34
	s_nop 1
	v_permlane32_swap_b32_e32 v34, v35
	v_max_f32_e32 v34, v34, v35
	v_cmp_lt_f32_e32 vcc, s88, v34
	s_cmp_lg_u64 vcc, 0
	s_cselect_b64 s[52:53], -1, 0
	s_cbranch_vccnz .LBB0_367

.LBB0_362:
	s_add_i32 s46, s1, 0x2000
	s_cmpk_lg_i32 s1, 0x4000
	s_cselect_b32 s46, s46, 0
	v_add_u32_e32 v187, s50, v249
	ds_read_b64_tr_b16 v[56:57], v187 offset:24576
	ds_read_b64_tr_b16 v[58:59], v187 offset:25088
	s_waitcnt lgkmcnt(9)
	v_mfma_f32_32x32x16_bf16 v[82:97], v[114:117], v[150:153], v[66:81]
	v_add_f32_e32 v34, v36, v37
	v_add_f32_e32 v34, v38, v34
	v_add_f32_e32 v34, v39, v34
	v_add_f32_e32 v34, v40, v34
	v_add_f32_e32 v34, v41, v34
	v_cvt_pk_bf16_f32 v158, v36, v37
	v_cvt_pk_bf16_f32 v159, v38, v39
	ds_read_b64_tr_b16 v[52:53], v187 offset:28672
	ds_read_b64_tr_b16 v[54:55], v187 offset:29184
	v_add_f32_e32 v34, v42, v34
	v_add_f32_e32 v34, v43, v34
	v_add_f32_e32 v34, v44, v34
	v_add_f32_e32 v38, v45, v34
	v_cvt_pk_bf16_f32 v160, v40, v41
	v_cvt_pk_bf16_f32 v161, v42, v43
	s_waitcnt lgkmcnt(10)
	v_mfma_f32_32x32x16_bf16 v[114:129], v[178:181], v[150:153], v[66:81]
	ds_read_b64_tr_b16 v[34:35], v187 offset:25600
	ds_read_b64_tr_b16 v[36:37], v187 offset:26112
	s_waitcnt lgkmcnt(11)
	v_mfma_f32_32x32x16_bf16 v[82:97], v[182:185], v[142:145], v[82:97]
	v_add_f32_e32 v38, v46, v38
	v_add_f32_e32 v38, v47, v38
	v_add_f32_e32 v38, v48, v38
	v_add_f32_e32 v42, v49, v38
	v_cvt_pk_bf16_f32 v154, v44, v45
	v_cvt_pk_bf16_f32 v155, v46, v47
	ds_read_b64_tr_b16 v[38:39], v187 offset:29696
	ds_read_b64_tr_b16 v[40:41], v187 offset:30208
	v_add_f32_e32 v42, v50, v42
	v_add_f32_e32 v42, v51, v42
	v_add_f32_e32 v42, v98, v42
	v_add_f32_e32 v46, v99, v42
	v_cvt_pk_bf16_f32 v156, v48, v49
	v_cvt_pk_bf16_f32 v157, v50, v51
	s_waitcnt lgkmcnt(12)
	v_mfma_f32_32x32x16_bf16 v[114:129], v[174:177], v[142:145], v[114:129]
	ds_read_b64_tr_b16 v[42:43], v187 offset:26624
	ds_read_b64_tr_b16 v[44:45], v187 offset:27136
	s_waitcnt lgkmcnt(13)
	v_mfma_f32_32x32x16_bf16 v[82:97], v[170:173], v[134:137], v[82:97]
	v_add_f32_e32 v46, v100, v46
	v_add_f32_e32 v46, v101, v46
	v_add_f32_e32 v46, v102, v46
	v_add_f32_e32 v50, v103, v46
	v_cvt_pk_bf16_f32 v146, v98, v99
	v_cvt_pk_bf16_f32 v147, v100, v101
	ds_read_b64_tr_b16 v[46:47], v187 offset:30720
	ds_read_b64_tr_b16 v[48:49], v187 offset:31232
	v_add_f32_e32 v50, v104, v50
	v_add_f32_e32 v50, v105, v50
	v_add_f32_e32 v50, v106, v50
	v_add_f32_e32 v50, v107, v50
	v_cvt_pk_bf16_f32 v148, v102, v103
	v_cvt_pk_bf16_f32 v149, v104, v105
	s_waitcnt lgkmcnt(14)
	v_mfma_f32_32x32x16_bf16 v[114:129], v[60:63], v[134:137], v[114:129]
	ds_read_b64_tr_b16 v[60:61], v187 offset:27648
	ds_read_b64_tr_b16 v[62:63], v187 offset:28160
	s_waitcnt lgkmcnt(14)
	v_mfma_f32_32x32x16_bf16 v[82:97], v[166:169], v[130:133], v[82:97]
	v_add_f32_e32 v50, v108, v50
	v_add_f32_e32 v50, v109, v50
	v_add_f32_e32 v50, v110, v50
	v_add_f32_e32 v50, v111, v50
	v_cvt_pk_bf16_f32 v138, v106, v107
	v_cvt_pk_bf16_f32 v139, v108, v109
	ds_read_b64_tr_b16 v[194:195], v187 offset:31744
	ds_read_b64_tr_b16 v[196:197], v187 offset:32256
	v_add_f32_e32 v50, v112, v50
	v_add_f32_e32 v50, v113, v50
	v_cvt_pk_bf16_f32 v140, v110, v111
	v_cvt_pk_bf16_f32 v141, v112, v113
	v_mfma_f32_32x32x16_bf16 v[114:129], v[162:165], v[130:133], v[114:129]
	s_nop 10
	v_pk_add_f32 v[98:99], v[220:221], v[114:115]
	v_pk_add_f32 v[100:101], v[214:215], v[116:117]
	v_max_f32_e32 v51, v82, v83
	v_max3_f32 v114, v84, v85, v99
	v_max3_f32 v51, v51, v98, v100
	v_pk_add_f32 v[104:105], v[214:215], v[120:121]
	v_pk_add_f32 v[102:103], v[214:215], v[118:119]
	v_max3_f32 v51, v51, v101, v86
	v_max3_f32 v114, v114, v88, v89
	v_max3_f32 v51, v51, v87, v102
	v_max3_f32 v114, v114, v104, v105
	v_pk_add_f32 v[108:109], v[214:215], v[124:125]
	v_pk_add_f32 v[106:107], v[214:215], v[122:123]
	v_max3_f32 v51, v51, v103, v90
	v_max3_f32 v114, v114, v92, v93
	v_max3_f32 v51, v51, v91, v106
	v_max3_f32 v114, v114, v108, v109
	v_pk_add_f32 v[112:113], v[214:215], v[128:129]
	v_pk_add_f32 v[110:111], v[214:215], v[126:127]
	v_max3_f32 v51, v51, v107, v94
	v_max3_f32 v114, v114, v96, v97
	v_max3_f32 v51, v51, v95, v110
	v_max3_f32 v114, v114, v112, v113
	v_max3_f32 v51, v51, v111, v114
	v_mov_b32_e32 v114, v51
	s_nop 1
	v_permlane32_swap_b32_e32 v51, v114
	s_add_i32 s48, s1, s29
	s_mov_b32 s50, m0
	s_mov_b32 m0, s48
	s_nop 0
	global_load_lds_dwordx4 v[224:225], off
	s_mov_b32 m0, s50
	v_max_f32_e32 v51, v51, v114
	s_add_i32 s48, s46, s44
	s_mov_b32 s50, m0
	s_mov_b32 m0, s48
	s_nop 0
	global_load_lds_dwordx4 v[222:223], off
	s_mov_b32 m0, s50
	v_cmp_lt_f32_e32 vcc, s88, v51
	s_cmp_lg_u64 vcc, 0
	v_fmac_f32_e32 v50, v210, v186
	s_cselect_b64 s[52:53], -1, 0
	s_cbranch_vccnz .LBB0_370
.LBB0_363:
	v_pk_mul_f32 v[32:33], v[210:211], v[32:33]
	v_pk_mul_f32 v[30:31], v[210:211], v[30:31]
	v_pk_mul_f32 v[28:29], v[210:211], v[28:29]
	v_pk_mul_f32 v[26:27], v[210:211], v[26:27]
	v_pk_mul_f32 v[24:25], v[210:211], v[24:25]
	v_pk_mul_f32 v[22:23], v[210:211], v[22:23]
	v_pk_mul_f32 v[20:21], v[210:211], v[20:21]
	v_pk_mul_f32 v[18:19], v[64:65], v[18:19]
	v_pk_mul_f32 v[16:17], v[210:211], v[16:17]
	v_pk_mul_f32 v[14:15], v[210:211], v[14:15]
	v_pk_mul_f32 v[12:13], v[210:211], v[12:13]
	v_pk_mul_f32 v[10:11], v[210:211], v[10:11]
	v_pk_mul_f32 v[8:9], v[210:211], v[8:9]
	v_pk_mul_f32 v[6:7], v[210:211], v[6:7]
	v_pk_mul_f32 v[4:5], v[210:211], v[4:5]
	v_pk_mul_f32 v[2:3], v[64:65], v[2:3]
	s_waitcnt lgkmcnt(14)
	s_nop 0
	v_mfma_f32_32x32x16_bf16 v[2:17], v[158:161], v[56:59], v[2:17]
	v_exp_f32_e32 v82, v82
	v_exp_f32_e32 v83, v83
	v_exp_f32_e32 v84, v84
	v_exp_f32_e32 v85, v85
	s_waitcnt lgkmcnt(12)
	v_mfma_f32_32x32x16_bf16 v[18:33], v[158:161], v[52:55], v[18:33]
	v_exp_f32_e32 v86, v86
	v_exp_f32_e32 v87, v87
	v_exp_f32_e32 v88, v88
	v_exp_f32_e32 v89, v89
	v_add_u32_e32 v51, s46, v248
	ds_read_b128 v[190:193], v51
	ds_read_b128 v[186:189], v51 offset:512
	s_waitcnt lgkmcnt(12)
	v_mfma_f32_32x32x16_bf16 v[2:17], v[154:157], v[34:37], v[2:17]
	v_exp_f32_e32 v90, v90
	v_exp_f32_e32 v91, v91
	v_exp_f32_e32 v92, v92
	v_exp_f32_e32 v93, v93
	ds_read_b128 v[182:185], v51 offset:2048
	ds_read_b128 v[178:181], v51 offset:2560
	s_waitcnt lgkmcnt(12)
	v_mfma_f32_32x32x16_bf16 v[18:33], v[154:157], v[38:41], v[18:33]
	v_exp_f32_e32 v94, v94
	v_exp_f32_e32 v95, v95
	v_exp_f32_e32 v96, v96
	v_exp_f32_e32 v97, v97
	ds_read_b128 v[174:177], v51 offset:4096
	ds_read_b128 v[170:173], v51 offset:4608
	s_waitcnt lgkmcnt(12)
	v_mfma_f32_32x32x16_bf16 v[2:17], v[146:149], v[42:45], v[2:17]
	v_exp_f32_e32 v98, v98
	v_exp_f32_e32 v99, v99
	v_exp_f32_e32 v100, v100
	v_exp_f32_e32 v101, v101
	ds_read_b128 v[166:169], v51 offset:6144
	ds_read_b128 v[162:165], v51 offset:6656
	s_waitcnt lgkmcnt(12)
	v_mfma_f32_32x32x16_bf16 v[18:33], v[146:149], v[46:49], v[18:33]
	v_exp_f32_e32 v102, v102
	v_exp_f32_e32 v103, v103
	v_exp_f32_e32 v104, v104
	v_exp_f32_e32 v105, v105
	s_waitcnt lgkmcnt(10)
	v_mfma_f32_32x32x16_bf16 v[2:17], v[138:141], v[60:63], v[2:17]
	v_exp_f32_e32 v106, v106
	v_exp_f32_e32 v107, v107
	v_exp_f32_e32 v108, v108
	v_exp_f32_e32 v109, v109
	s_waitcnt lgkmcnt(8)
	v_mfma_f32_32x32x16_bf16 v[18:33], v[138:141], v[194:197], v[18:33]
	v_exp_f32_e32 v110, v110
	v_exp_f32_e32 v111, v111
	v_exp_f32_e32 v112, v112
	v_exp_f32_e32 v113, v113
	s_waitcnt vmcnt(2) lgkmcnt(0)
	s_barrier
	s_andn2_b64 vcc, exec, s[52:53]
	s_cbranch_vccnz .LBB0_365
	s_waitcnt lgkmcnt(0)
	ds_read_b128 v[34:37], v242 offset:49248
	ds_read_b128 v[38:41], v242 offset:49216
	ds_read_b128 v[42:45], v242 offset:49184
	ds_read_b128 v[46:49], v242 offset:49152
	s_waitcnt lgkmcnt(3)
	v_pk_mul_f32 v[16:17], v[16:17], v[36:37]
	s_waitcnt lgkmcnt(2)
	v_pk_mul_f32 v[12:13], v[12:13], v[40:41]
	s_waitcnt lgkmcnt(1)
	v_pk_mul_f32 v[8:9], v[8:9], v[44:45]
	s_waitcnt lgkmcnt(0)
	v_pk_mul_f32 v[4:5], v[4:5], v[48:49]
	v_pk_mul_f32 v[14:15], v[14:15], v[34:35]
	v_pk_mul_f32 v[10:11], v[10:11], v[38:39]
	v_pk_mul_f32 v[6:7], v[6:7], v[42:43]
	v_pk_mul_f32 v[2:3], v[2:3], v[46:47]
	v_pk_mul_f32 v[32:33], v[32:33], v[36:37]
	v_pk_mul_f32 v[28:29], v[28:29], v[40:41]
	v_pk_mul_f32 v[24:25], v[24:25], v[44:45]
	v_pk_mul_f32 v[20:21], v[20:21], v[48:49]
	v_pk_mul_f32 v[30:31], v[30:31], v[34:35]
	v_pk_mul_f32 v[26:27], v[26:27], v[38:39]
	v_pk_mul_f32 v[22:23], v[22:23], v[42:43]
	v_pk_mul_f32 v[18:19], v[18:19], v[46:47]
